# P0-adaLN-items-reversed
# speedup vs baseline: 1.0228x; 1.0022x over previous
; #define X make_ctx(lds_raw)
; __device__ __forceinline__ void phase0(const Ctx& X, KArgs a) {
;     ...
;       for (int u = X.gw; u < 96 * 32; u += X.ngw) { const int cgp = u % 96, kc = u / 96, j = cgp * 64 + X.lane;
;           float w[32];
; #pragma unroll
;           for (int kk = 0; kk < 32; ++kk) w[kk] = __builtin_nontemporal_load(&a->ada_w[(size_t)(kc * 32 + kk) * 6144 + j]);
;           const float cA = a->c[(X.lane >> 5) * DM + kc * 32 + (X.lane & 31)], cB = a->c[((X.lane >> 5) + 2) * DM + kc * 32 + (X.lane & 31)];
;           const int sA = __float_as_int(cA / (1.0f + __expf(-cA))), sB = __float_as_int(cB / (1.0f + __expf(-cB)));
;           float acc[4] = {0.f, 0.f, 0.f, 0.f};
; #pragma unroll
;           for (int kk = 0; kk < 32; ++kk) {
;               acc[0] += __int_as_float(__builtin_amdgcn_readlane(sA, kk)) * w[kk]; acc[1] += __int_as_float(__builtin_amdgcn_readlane(sA, 32 + kk)) * w[kk];
;               acc[2] += __int_as_float(__builtin_amdgcn_readlane(sB, kk)) * w[kk]; acc[3] += __int_as_float(__builtin_amdgcn_readlane(sB, 32 + kk)) * w[kk]; }
; #pragma unroll
;           for (int b = 0; b < 4; ++b) modp[(size_t)(kc * 4 + b) * 6144 + j] = acc[b]; } }
.LBB0_13:
	s_waitcnt lgkmcnt(0)
	v_writelane_b32 v254, s20, 5
	s_nop 1
	v_writelane_b32 v254, s21, 6
	s_or_b64 exec, exec, s[8:9]
	s_ashr_i32 s4, s16, 6
	s_lshl_b32 s5, s82, 3
	s_add_i32 s14, s4, s5
	s_lshl_b32 s83, s84, 3
	s_sub_i32 s14, s83, s14
	s_add_i32 s14, s14, -1
	v_writelane_b32 v254, s5, 7
	s_cmpk_gt_i32 s14, 0xbff
	v_and_b32_e32 v1, 31, v10
	s_cbranch_scc1 .LBB0_16
	s_load_dwordx2 s[10:11], s[6:7], 0x8
	s_load_dwordx2 s[12:13], s[6:7], 0x18
	v_lshlrev_b32_e32 v3, 5, v10
	s_movk_i32 s4, 0x400
	s_add_u32 s8, s2, 0x300000
	v_and_b32_e32 v4, 63, v10
	v_and_or_b32 v3, v3, s4, v1
	s_addc_u32 s9, s3, 0
	v_or_b32_e32 v12, 0x800, v3
	v_lshl_or_b32 v13, s14, 6, v4
	s_lshl_b32 s15, s83, 6
	v_mov_b32_e32 v14, 0x6000
